# adaLN partial sums (P0): 16 weight-row loads in flight per trip instead of 4
# baseline (speedup 1.0000x reference)
; __global__ void __launch_bounds__(512, 2) fwd_mega(Args args) {
;     ...
;             const float* wp = w_ada + (size_t)(kpart * 64) * NMOD + 4 * cgp;
; #pragma unroll 4
;             for (int kk = 0; kk < 64; ++kk) { const f32x4 w = __builtin_nontemporal_load((const f32x4*)(wp + (size_t)kk * NMOD));
; #pragma unroll
;                 for (int v = 0; v < 5; ++v) acc[v] += w * sv[v * 64 + kk]; }
.LBB0_11:
	s_mov_b32 s98, 0xc000
	s_mov_b32 s99, 0
	v_lshl_add_u64 v[38:39], v[26:27], 0, s[24:25]
	global_load_dwordx4 v[80:83], v[38:39], off nt
	v_lshl_add_u64 v[38:39], v[38:39], 0, s[98:99]
	global_load_dwordx4 v[84:87], v[38:39], off nt
	v_lshl_add_u64 v[38:39], v[38:39], 0, s[98:99]
	global_load_dwordx4 v[88:91], v[38:39], off nt
	v_lshl_add_u64 v[38:39], v[38:39], 0, s[98:99]
	global_load_dwordx4 v[92:95], v[38:39], off nt
	v_lshl_add_u64 v[38:39], v[38:39], 0, s[98:99]
	global_load_dwordx4 v[96:99], v[38:39], off nt
	v_lshl_add_u64 v[38:39], v[38:39], 0, s[98:99]
	global_load_dwordx4 v[100:103], v[38:39], off nt
	v_lshl_add_u64 v[38:39], v[38:39], 0, s[98:99]
	global_load_dwordx4 v[104:107], v[38:39], off nt
	v_lshl_add_u64 v[38:39], v[38:39], 0, s[98:99]
	global_load_dwordx4 v[108:111], v[38:39], off nt
	v_lshl_add_u64 v[38:39], v[38:39], 0, s[98:99]
	global_load_dwordx4 v[112:115], v[38:39], off nt
	v_lshl_add_u64 v[38:39], v[38:39], 0, s[98:99]
	global_load_dwordx4 v[116:119], v[38:39], off nt
	v_lshl_add_u64 v[38:39], v[38:39], 0, s[98:99]
	global_load_dwordx4 v[126:129], v[38:39], off nt
	v_lshl_add_u64 v[38:39], v[38:39], 0, s[98:99]
	global_load_dwordx4 v[130:133], v[38:39], off nt
	v_lshl_add_u64 v[38:39], v[38:39], 0, s[98:99]
	global_load_dwordx4 v[134:137], v[38:39], off nt
	v_lshl_add_u64 v[38:39], v[38:39], 0, s[98:99]
	global_load_dwordx4 v[138:141], v[38:39], off nt
	v_lshl_add_u64 v[38:39], v[38:39], 0, s[98:99]
	global_load_dwordx4 v[142:145], v[38:39], off nt
	v_lshl_add_u64 v[38:39], v[38:39], 0, s[98:99]
	global_load_dwordx4 v[146:149], v[38:39], off nt
	v_mov_b32_e32 v33, s18
	ds_read_b128 v[50:53], v33
	ds_read_b128 v[54:57], v33 offset:256
	ds_read_b128 v[58:61], v33 offset:512
	ds_read_b128 v[62:65], v33 offset:768
	ds_read_b128 v[66:69], v33 offset:1024
	s_add_i32 s18, s18, 16
	s_waitcnt lgkmcnt(0)
	v_mov_b32_e32 v70, v53
	v_mov_b32_e32 v72, v57
	v_mov_b32_e32 v74, v61
	v_mov_b32_e32 v76, v65
	v_mov_b32_e32 v78, v69
	s_waitcnt vmcnt(15)
	v_pk_fma_f32 v[20:21], v[82:83], v[50:51], v[20:21] op_sel_hi:[1,0,1]
	v_pk_fma_f32 v[18:19], v[80:81], v[50:51], v[18:19] op_sel_hi:[1,0,1]
	v_pk_fma_f32 v[16:17], v[82:83], v[54:55], v[16:17] op_sel_hi:[1,0,1]
	v_pk_fma_f32 v[14:15], v[80:81], v[54:55], v[14:15] op_sel_hi:[1,0,1]
	v_pk_fma_f32 v[12:13], v[82:83], v[58:59], v[12:13] op_sel_hi:[1,0,1]
	v_pk_fma_f32 v[10:11], v[80:81], v[58:59], v[10:11] op_sel_hi:[1,0,1]
	v_pk_fma_f32 v[8:9], v[82:83], v[62:63], v[8:9] op_sel_hi:[1,0,1]
	v_pk_fma_f32 v[6:7], v[80:81], v[62:63], v[6:7] op_sel_hi:[1,0,1]
	v_pk_fma_f32 v[4:5], v[82:83], v[66:67], v[4:5] op_sel_hi:[1,0,1]
	v_pk_fma_f32 v[2:3], v[80:81], v[66:67], v[2:3] op_sel_hi:[1,0,1]
	s_waitcnt vmcnt(14)
	v_pk_fma_f32 v[18:19], v[84:85], v[50:51], v[18:19] op_sel:[0,1,0]
	v_pk_fma_f32 v[20:21], v[86:87], v[50:51], v[20:21] op_sel:[0,1,0]
	v_pk_fma_f32 v[14:15], v[84:85], v[54:55], v[14:15] op_sel:[0,1,0]
	v_pk_fma_f32 v[16:17], v[86:87], v[54:55], v[16:17] op_sel:[0,1,0]
	v_pk_fma_f32 v[10:11], v[84:85], v[58:59], v[10:11] op_sel:[0,1,0]
	v_pk_fma_f32 v[12:13], v[86:87], v[58:59], v[12:13] op_sel:[0,1,0]
	v_pk_fma_f32 v[6:7], v[84:85], v[62:63], v[6:7] op_sel:[0,1,0]
	v_pk_fma_f32 v[8:9], v[86:87], v[62:63], v[8:9] op_sel:[0,1,0]
	v_pk_fma_f32 v[2:3], v[84:85], v[66:67], v[2:3] op_sel:[0,1,0]
	v_pk_fma_f32 v[4:5], v[86:87], v[66:67], v[4:5] op_sel:[0,1,0]
	s_waitcnt vmcnt(13)
	v_pk_fma_f32 v[20:21], v[90:91], v[52:53], v[20:21] op_sel_hi:[1,0,1]
	v_pk_fma_f32 v[18:19], v[88:89], v[52:53], v[18:19] op_sel_hi:[1,0,1]
	v_pk_fma_f32 v[16:17], v[90:91], v[56:57], v[16:17] op_sel_hi:[1,0,1]
	v_pk_fma_f32 v[14:15], v[88:89], v[56:57], v[14:15] op_sel_hi:[1,0,1]
	v_pk_fma_f32 v[12:13], v[90:91], v[60:61], v[12:13] op_sel_hi:[1,0,1]
	v_pk_fma_f32 v[10:11], v[88:89], v[60:61], v[10:11] op_sel_hi:[1,0,1]
	v_pk_fma_f32 v[8:9], v[90:91], v[64:65], v[8:9] op_sel_hi:[1,0,1]
	v_pk_fma_f32 v[6:7], v[88:89], v[64:65], v[6:7] op_sel_hi:[1,0,1]
	v_pk_fma_f32 v[4:5], v[90:91], v[68:69], v[4:5] op_sel_hi:[1,0,1]
	v_pk_fma_f32 v[2:3], v[88:89], v[68:69], v[2:3] op_sel_hi:[1,0,1]
	s_waitcnt vmcnt(12)
	v_pk_fma_f32 v[20:21], v[94:95], v[70:71], v[20:21] op_sel_hi:[1,0,1]
	v_pk_fma_f32 v[18:19], v[92:93], v[70:71], v[18:19] op_sel_hi:[1,0,1]
	v_pk_fma_f32 v[16:17], v[94:95], v[72:73], v[16:17] op_sel_hi:[1,0,1]
	v_pk_fma_f32 v[14:15], v[92:93], v[72:73], v[14:15] op_sel_hi:[1,0,1]
	v_pk_fma_f32 v[12:13], v[94:95], v[74:75], v[12:13] op_sel_hi:[1,0,1]
	v_pk_fma_f32 v[10:11], v[92:93], v[74:75], v[10:11] op_sel_hi:[1,0,1]
	v_pk_fma_f32 v[8:9], v[94:95], v[76:77], v[8:9] op_sel_hi:[1,0,1]
	v_pk_fma_f32 v[6:7], v[92:93], v[76:77], v[6:7] op_sel_hi:[1,0,1]
	v_pk_fma_f32 v[4:5], v[94:95], v[78:79], v[4:5] op_sel_hi:[1,0,1]
	v_pk_fma_f32 v[2:3], v[92:93], v[78:79], v[2:3] op_sel_hi:[1,0,1]
	v_mov_b32_e32 v33, s18
	ds_read_b128 v[50:53], v33
	ds_read_b128 v[54:57], v33 offset:256
	ds_read_b128 v[58:61], v33 offset:512
	ds_read_b128 v[62:65], v33 offset:768
	ds_read_b128 v[66:69], v33 offset:1024
	s_add_i32 s18, s18, 16
	s_waitcnt lgkmcnt(0)
	v_mov_b32_e32 v70, v53
	v_mov_b32_e32 v72, v57
	v_mov_b32_e32 v74, v61
	v_mov_b32_e32 v76, v65
	v_mov_b32_e32 v78, v69
	s_waitcnt vmcnt(11)
	v_pk_fma_f32 v[20:21], v[98:99], v[50:51], v[20:21] op_sel_hi:[1,0,1]
	v_pk_fma_f32 v[18:19], v[96:97], v[50:51], v[18:19] op_sel_hi:[1,0,1]
	v_pk_fma_f32 v[16:17], v[98:99], v[54:55], v[16:17] op_sel_hi:[1,0,1]
	v_pk_fma_f32 v[14:15], v[96:97], v[54:55], v[14:15] op_sel_hi:[1,0,1]
	v_pk_fma_f32 v[12:13], v[98:99], v[58:59], v[12:13] op_sel_hi:[1,0,1]
	v_pk_fma_f32 v[10:11], v[96:97], v[58:59], v[10:11] op_sel_hi:[1,0,1]
	v_pk_fma_f32 v[8:9], v[98:99], v[62:63], v[8:9] op_sel_hi:[1,0,1]
	v_pk_fma_f32 v[6:7], v[96:97], v[62:63], v[6:7] op_sel_hi:[1,0,1]
	v_pk_fma_f32 v[4:5], v[98:99], v[66:67], v[4:5] op_sel_hi:[1,0,1]
	v_pk_fma_f32 v[2:3], v[96:97], v[66:67], v[2:3] op_sel_hi:[1,0,1]
	s_waitcnt vmcnt(10)
; __global__ void __launch_bounds__(512, 2) fwd_mega(Args args) {
;     ...
;             const float* wp = w_ada + (size_t)(kpart * 64) * NMOD + 4 * cgp;
; #pragma unroll 4
;             for (int kk = 0; kk < 64; ++kk) { const f32x4 w = __builtin_nontemporal_load((const f32x4*)(wp + (size_t)kk * NMOD));
; #pragma unroll
;                 for (int v = 0; v < 5; ++v) acc[v] += w * sv[v * 64 + kk]; }
	v_pk_fma_f32 v[18:19], v[100:101], v[50:51], v[18:19] op_sel:[0,1,0]
	v_pk_fma_f32 v[20:21], v[102:103], v[50:51], v[20:21] op_sel:[0,1,0]
	v_pk_fma_f32 v[14:15], v[100:101], v[54:55], v[14:15] op_sel:[0,1,0]
	v_pk_fma_f32 v[16:17], v[102:103], v[54:55], v[16:17] op_sel:[0,1,0]
	v_pk_fma_f32 v[10:11], v[100:101], v[58:59], v[10:11] op_sel:[0,1,0]
	v_pk_fma_f32 v[12:13], v[102:103], v[58:59], v[12:13] op_sel:[0,1,0]
	v_pk_fma_f32 v[6:7], v[100:101], v[62:63], v[6:7] op_sel:[0,1,0]
	v_pk_fma_f32 v[8:9], v[102:103], v[62:63], v[8:9] op_sel:[0,1,0]
	v_pk_fma_f32 v[2:3], v[100:101], v[66:67], v[2:3] op_sel:[0,1,0]
	v_pk_fma_f32 v[4:5], v[102:103], v[66:67], v[4:5] op_sel:[0,1,0]
	s_waitcnt vmcnt(9)
	v_pk_fma_f32 v[20:21], v[106:107], v[52:53], v[20:21] op_sel_hi:[1,0,1]
	v_pk_fma_f32 v[18:19], v[104:105], v[52:53], v[18:19] op_sel_hi:[1,0,1]
	v_pk_fma_f32 v[16:17], v[106:107], v[56:57], v[16:17] op_sel_hi:[1,0,1]
	v_pk_fma_f32 v[14:15], v[104:105], v[56:57], v[14:15] op_sel_hi:[1,0,1]
	v_pk_fma_f32 v[12:13], v[106:107], v[60:61], v[12:13] op_sel_hi:[1,0,1]
	v_pk_fma_f32 v[10:11], v[104:105], v[60:61], v[10:11] op_sel_hi:[1,0,1]
	v_pk_fma_f32 v[8:9], v[106:107], v[64:65], v[8:9] op_sel_hi:[1,0,1]
	v_pk_fma_f32 v[6:7], v[104:105], v[64:65], v[6:7] op_sel_hi:[1,0,1]
	v_pk_fma_f32 v[4:5], v[106:107], v[68:69], v[4:5] op_sel_hi:[1,0,1]
	v_pk_fma_f32 v[2:3], v[104:105], v[68:69], v[2:3] op_sel_hi:[1,0,1]
	s_waitcnt vmcnt(8)
	v_pk_fma_f32 v[20:21], v[110:111], v[70:71], v[20:21] op_sel_hi:[1,0,1]
	v_pk_fma_f32 v[18:19], v[108:109], v[70:71], v[18:19] op_sel_hi:[1,0,1]
	v_pk_fma_f32 v[16:17], v[110:111], v[72:73], v[16:17] op_sel_hi:[1,0,1]
	v_pk_fma_f32 v[14:15], v[108:109], v[72:73], v[14:15] op_sel_hi:[1,0,1]
	v_pk_fma_f32 v[12:13], v[110:111], v[74:75], v[12:13] op_sel_hi:[1,0,1]
	v_pk_fma_f32 v[10:11], v[108:109], v[74:75], v[10:11] op_sel_hi:[1,0,1]
	v_pk_fma_f32 v[8:9], v[110:111], v[76:77], v[8:9] op_sel_hi:[1,0,1]
	v_pk_fma_f32 v[6:7], v[108:109], v[76:77], v[6:7] op_sel_hi:[1,0,1]
	v_pk_fma_f32 v[4:5], v[110:111], v[78:79], v[4:5] op_sel_hi:[1,0,1]
	v_pk_fma_f32 v[2:3], v[108:109], v[78:79], v[2:3] op_sel_hi:[1,0,1]
	v_mov_b32_e32 v33, s18
	ds_read_b128 v[50:53], v33
	ds_read_b128 v[54:57], v33 offset:256
	ds_read_b128 v[58:61], v33 offset:512
	ds_read_b128 v[62:65], v33 offset:768
	ds_read_b128 v[66:69], v33 offset:1024
	s_add_i32 s18, s18, 16
	s_waitcnt lgkmcnt(0)
	v_mov_b32_e32 v70, v53
	v_mov_b32_e32 v72, v57
	v_mov_b32_e32 v74, v61
	v_mov_b32_e32 v76, v65
	v_mov_b32_e32 v78, v69
	s_waitcnt vmcnt(7)
	v_pk_fma_f32 v[20:21], v[114:115], v[50:51], v[20:21] op_sel_hi:[1,0,1]
	v_pk_fma_f32 v[18:19], v[112:113], v[50:51], v[18:19] op_sel_hi:[1,0,1]
	v_pk_fma_f32 v[16:17], v[114:115], v[54:55], v[16:17] op_sel_hi:[1,0,1]
	v_pk_fma_f32 v[14:15], v[112:113], v[54:55], v[14:15] op_sel_hi:[1,0,1]
	v_pk_fma_f32 v[12:13], v[114:115], v[58:59], v[12:13] op_sel_hi:[1,0,1]
	v_pk_fma_f32 v[10:11], v[112:113], v[58:59], v[10:11] op_sel_hi:[1,0,1]
	v_pk_fma_f32 v[8:9], v[114:115], v[62:63], v[8:9] op_sel_hi:[1,0,1]
	v_pk_fma_f32 v[6:7], v[112:113], v[62:63], v[6:7] op_sel_hi:[1,0,1]
	v_pk_fma_f32 v[4:5], v[114:115], v[66:67], v[4:5] op_sel_hi:[1,0,1]
	v_pk_fma_f32 v[2:3], v[112:113], v[66:67], v[2:3] op_sel_hi:[1,0,1]
	s_waitcnt vmcnt(6)
	v_pk_fma_f32 v[18:19], v[116:117], v[50:51], v[18:19] op_sel:[0,1,0]
	v_pk_fma_f32 v[20:21], v[118:119], v[50:51], v[20:21] op_sel:[0,1,0]
	v_pk_fma_f32 v[14:15], v[116:117], v[54:55], v[14:15] op_sel:[0,1,0]
	v_pk_fma_f32 v[16:17], v[118:119], v[54:55], v[16:17] op_sel:[0,1,0]
	v_pk_fma_f32 v[10:11], v[116:117], v[58:59], v[10:11] op_sel:[0,1,0]
	v_pk_fma_f32 v[12:13], v[118:119], v[58:59], v[12:13] op_sel:[0,1,0]
	v_pk_fma_f32 v[6:7], v[116:117], v[62:63], v[6:7] op_sel:[0,1,0]
	v_pk_fma_f32 v[8:9], v[118:119], v[62:63], v[8:9] op_sel:[0,1,0]
	v_pk_fma_f32 v[2:3], v[116:117], v[66:67], v[2:3] op_sel:[0,1,0]
	v_pk_fma_f32 v[4:5], v[118:119], v[66:67], v[4:5] op_sel:[0,1,0]
	s_waitcnt vmcnt(5)
	v_pk_fma_f32 v[20:21], v[128:129], v[52:53], v[20:21] op_sel_hi:[1,0,1]
	v_pk_fma_f32 v[18:19], v[126:127], v[52:53], v[18:19] op_sel_hi:[1,0,1]
	v_pk_fma_f32 v[16:17], v[128:129], v[56:57], v[16:17] op_sel_hi:[1,0,1]
	v_pk_fma_f32 v[14:15], v[126:127], v[56:57], v[14:15] op_sel_hi:[1,0,1]
	v_pk_fma_f32 v[12:13], v[128:129], v[60:61], v[12:13] op_sel_hi:[1,0,1]
	v_pk_fma_f32 v[10:11], v[126:127], v[60:61], v[10:11] op_sel_hi:[1,0,1]
	v_pk_fma_f32 v[8:9], v[128:129], v[64:65], v[8:9] op_sel_hi:[1,0,1]
	v_pk_fma_f32 v[6:7], v[126:127], v[64:65], v[6:7] op_sel_hi:[1,0,1]
	v_pk_fma_f32 v[4:5], v[128:129], v[68:69], v[4:5] op_sel_hi:[1,0,1]
	v_pk_fma_f32 v[2:3], v[126:127], v[68:69], v[2:3] op_sel_hi:[1,0,1]
	s_waitcnt vmcnt(4)
; __global__ void __launch_bounds__(512, 2) fwd_mega(Args args) {
;     ...
;             const float* wp = w_ada + (size_t)(kpart * 64) * NMOD + 4 * cgp;
; #pragma unroll 4
;             for (int kk = 0; kk < 64; ++kk) { const f32x4 w = __builtin_nontemporal_load((const f32x4*)(wp + (size_t)kk * NMOD));
; #pragma unroll
;                 for (int v = 0; v < 5; ++v) acc[v] += w * sv[v * 64 + kk]; }
; #pragma unroll
;             for (int v = 0; v < 5; ++v) *(f32x4*)(part + (size_t)(kpart * 5 + v) * NMOD + 4 * cgp) = acc[v];
;             __syncthreads();
	v_pk_fma_f32 v[20:21], v[132:133], v[70:71], v[20:21] op_sel_hi:[1,0,1]
	v_pk_fma_f32 v[18:19], v[130:131], v[70:71], v[18:19] op_sel_hi:[1,0,1]
	v_pk_fma_f32 v[16:17], v[132:133], v[72:73], v[16:17] op_sel_hi:[1,0,1]
	v_pk_fma_f32 v[14:15], v[130:131], v[72:73], v[14:15] op_sel_hi:[1,0,1]
	v_pk_fma_f32 v[12:13], v[132:133], v[74:75], v[12:13] op_sel_hi:[1,0,1]
	v_pk_fma_f32 v[10:11], v[130:131], v[74:75], v[10:11] op_sel_hi:[1,0,1]
	v_pk_fma_f32 v[8:9], v[132:133], v[76:77], v[8:9] op_sel_hi:[1,0,1]
	v_pk_fma_f32 v[6:7], v[130:131], v[76:77], v[6:7] op_sel_hi:[1,0,1]
	v_pk_fma_f32 v[4:5], v[132:133], v[78:79], v[4:5] op_sel_hi:[1,0,1]
	v_pk_fma_f32 v[2:3], v[130:131], v[78:79], v[2:3] op_sel_hi:[1,0,1]
	v_mov_b32_e32 v33, s18
	ds_read_b128 v[50:53], v33
	ds_read_b128 v[54:57], v33 offset:256
	ds_read_b128 v[58:61], v33 offset:512
	ds_read_b128 v[62:65], v33 offset:768
	ds_read_b128 v[66:69], v33 offset:1024
	s_add_i32 s18, s18, 16
	s_waitcnt lgkmcnt(0)
	v_mov_b32_e32 v70, v53
	v_mov_b32_e32 v72, v57
	v_mov_b32_e32 v74, v61
	v_mov_b32_e32 v76, v65
	v_mov_b32_e32 v78, v69
	s_waitcnt vmcnt(3)
	v_pk_fma_f32 v[20:21], v[136:137], v[50:51], v[20:21] op_sel_hi:[1,0,1]
	v_pk_fma_f32 v[18:19], v[134:135], v[50:51], v[18:19] op_sel_hi:[1,0,1]
	v_pk_fma_f32 v[16:17], v[136:137], v[54:55], v[16:17] op_sel_hi:[1,0,1]
	v_pk_fma_f32 v[14:15], v[134:135], v[54:55], v[14:15] op_sel_hi:[1,0,1]
	v_pk_fma_f32 v[12:13], v[136:137], v[58:59], v[12:13] op_sel_hi:[1,0,1]
	v_pk_fma_f32 v[10:11], v[134:135], v[58:59], v[10:11] op_sel_hi:[1,0,1]
	v_pk_fma_f32 v[8:9], v[136:137], v[62:63], v[8:9] op_sel_hi:[1,0,1]
	v_pk_fma_f32 v[6:7], v[134:135], v[62:63], v[6:7] op_sel_hi:[1,0,1]
	v_pk_fma_f32 v[4:5], v[136:137], v[66:67], v[4:5] op_sel_hi:[1,0,1]
	v_pk_fma_f32 v[2:3], v[134:135], v[66:67], v[2:3] op_sel_hi:[1,0,1]
	s_waitcnt vmcnt(2)
	v_pk_fma_f32 v[18:19], v[138:139], v[50:51], v[18:19] op_sel:[0,1,0]
	v_pk_fma_f32 v[20:21], v[140:141], v[50:51], v[20:21] op_sel:[0,1,0]
	v_pk_fma_f32 v[14:15], v[138:139], v[54:55], v[14:15] op_sel:[0,1,0]
	v_pk_fma_f32 v[16:17], v[140:141], v[54:55], v[16:17] op_sel:[0,1,0]
	v_pk_fma_f32 v[10:11], v[138:139], v[58:59], v[10:11] op_sel:[0,1,0]
	v_pk_fma_f32 v[12:13], v[140:141], v[58:59], v[12:13] op_sel:[0,1,0]
	v_pk_fma_f32 v[6:7], v[138:139], v[62:63], v[6:7] op_sel:[0,1,0]
	v_pk_fma_f32 v[8:9], v[140:141], v[62:63], v[8:9] op_sel:[0,1,0]
	v_pk_fma_f32 v[2:3], v[138:139], v[66:67], v[2:3] op_sel:[0,1,0]
	v_pk_fma_f32 v[4:5], v[140:141], v[66:67], v[4:5] op_sel:[0,1,0]
	s_waitcnt vmcnt(1)
	v_pk_fma_f32 v[20:21], v[144:145], v[52:53], v[20:21] op_sel_hi:[1,0,1]
	v_pk_fma_f32 v[18:19], v[142:143], v[52:53], v[18:19] op_sel_hi:[1,0,1]
	v_pk_fma_f32 v[16:17], v[144:145], v[56:57], v[16:17] op_sel_hi:[1,0,1]
	v_pk_fma_f32 v[14:15], v[142:143], v[56:57], v[14:15] op_sel_hi:[1,0,1]
	v_pk_fma_f32 v[12:13], v[144:145], v[60:61], v[12:13] op_sel_hi:[1,0,1]
	v_pk_fma_f32 v[10:11], v[142:143], v[60:61], v[10:11] op_sel_hi:[1,0,1]
	v_pk_fma_f32 v[8:9], v[144:145], v[64:65], v[8:9] op_sel_hi:[1,0,1]
	v_pk_fma_f32 v[6:7], v[142:143], v[64:65], v[6:7] op_sel_hi:[1,0,1]
	v_pk_fma_f32 v[4:5], v[144:145], v[68:69], v[4:5] op_sel_hi:[1,0,1]
	v_pk_fma_f32 v[2:3], v[142:143], v[68:69], v[2:3] op_sel_hi:[1,0,1]
	s_waitcnt vmcnt(0)
	v_pk_fma_f32 v[20:21], v[148:149], v[70:71], v[20:21] op_sel_hi:[1,0,1]
	v_pk_fma_f32 v[18:19], v[146:147], v[70:71], v[18:19] op_sel_hi:[1,0,1]
	v_pk_fma_f32 v[16:17], v[148:149], v[72:73], v[16:17] op_sel_hi:[1,0,1]
	v_pk_fma_f32 v[14:15], v[146:147], v[72:73], v[14:15] op_sel_hi:[1,0,1]
	v_pk_fma_f32 v[12:13], v[148:149], v[74:75], v[12:13] op_sel_hi:[1,0,1]
	v_pk_fma_f32 v[10:11], v[146:147], v[74:75], v[10:11] op_sel_hi:[1,0,1]
	v_pk_fma_f32 v[8:9], v[148:149], v[76:77], v[8:9] op_sel_hi:[1,0,1]
	v_pk_fma_f32 v[6:7], v[146:147], v[76:77], v[6:7] op_sel_hi:[1,0,1]
	v_pk_fma_f32 v[4:5], v[148:149], v[78:79], v[4:5] op_sel_hi:[1,0,1]
	v_pk_fma_f32 v[2:3], v[146:147], v[78:79], v[2:3] op_sel_hi:[1,0,1]
	s_add_u32 s24, s24, 0xc0000
	s_addc_u32 s25, s25, 0
	s_cmp_eq_u32 s24, 0x300000
	s_cbranch_scc0 .LBB0_11
	s_mul_i32 s17, s17, 5
	v_lshl_add_u64 v[24:25], v[24:25], 2, s[22:23]
	v_mad_i64_i32 v[26:27], s[0:1], s17, v32, v[24:25]
	s_add_i32 s0, s17, 1
	global_store_dwordx4 v[26:27], v[18:21], off
	s_add_i32 s16, s16, s42
	s_nop 0
	v_mad_i64_i32 v[18:19], s[0:1], s0, v32, v[24:25]
	s_add_i32 s0, s17, 2
	global_store_dwordx4 v[18:19], v[14:17], off
	s_nop 1
	v_mad_i64_i32 v[14:15], s[0:1], s0, v32, v[24:25]
	s_add_i32 s0, s17, 3
	global_store_dwordx4 v[14:15], v[10:13], off
	s_add_i32 s17, s17, 4
	s_cmpk_gt_i32 s16, 0xbf
	v_mad_i64_i32 v[10:11], s[0:1], s0, v32, v[24:25]
	global_store_dwordx4 v[10:11], v[6:9], off
	s_nop 1
	v_mad_i64_i32 v[6:7], s[0:1], s17, v32, v[24:25]
	global_store_dwordx4 v[6:7], v[2:5], off
	s_barrier
	s_cbranch_scc0 .LBB0_8
